# pass C: the sample-stream unit (32 pad + 32 real tokens, always last of its sub-block) skips the all-pad query half
# speedup vs baseline: 1.0078x; 1.0051x over previous
; #define LAS __attribute__((address_space(3)))
; __device__ __forceinline__ void ssd_passC_unit(const Args& a, LAS unsigned char* lds, int unit, int tid, int w4, int lane, LAS unsigned* bcnt, unsigned& btarget) {
;     ...
;     const int h4 = w4, r = lane & 31, hf = lane >> 5, h = g * 4 + h4;
;     const LAS bf16_t* XT = (const LAS bf16_t*)(lds + L_XT) + h4 * 64 * XT_LD; const LAS bf16_t* Bn = (const LAS bf16_t*)(lds + L_BT); const LAS bf16_t* Cn = (const LAS bf16_t*)(lds + L_CN);
;     const LAS float* cs = (const LAS float*)(lds + L_CS) + h4 * 64; const LAS float* dtl = cs + 256; const LAS float* ecs = cs + 512; LAS float* red = (LAS float*)(lds + L_CS) + 768;
; #pragma unroll 1
;     for (int lh = 0; lh < 2; ++lh) {
;     const int l = lh * 32 + r;
;     const int row = si.row0 + l;
;     const bool realtok = l >= si.pad;
;     const bf16_t* zrow = (const bf16_t*)(a.ws + WS_PROJ) + (size_t)row * NPROJ + g * 256 + h4 * 64;
.LBB0_838:
	s_ashr_i32 s53, s52, 31
	s_or_b32 s17, s23, s18
	s_lshl_b64 s[0:1], s[52:53], 17
	s_lshl_b32 s20, s17, 14
	s_lshl_b32 s30, s16, 9
	s_add_u32 s0, s96, s0
	v_xor_b32_e32 v0, 32, v246
	v_add_u32_e32 v1, 64, v143
	s_addc_u32 s1, s97, s1
	v_cmp_lt_i32_e32 vcc, v0, v1
	s_add_u32 s0, s0, s20
	s_addc_u32 s1, s1, 0
	v_cndmask_b32_e32 v0, v246, v0, vcc
	v_mov_b32_e32 v143, v109
	v_lshlrev_b32_e32 v251, 2, v0
	v_lshl_add_u64 v[0:1], s[0:1], 0, v[142:143]
	v_mov_b32_e32 v147, v109
	v_lshl_add_u64 v[84:85], v[0:1], 0, v[146:147]
	s_lshl_b32 s0, s17, 2
	s_add_u32 s20, s78, s0
	s_addc_u32 s21, s79, 0
	s_lshl_b32 s0, s16, 10
	s_add_u32 s0, s80, s0
	s_addc_u32 s1, s81, 0
	v_mov_b32_e32 v145, v109
	s_add_u32 s52, s28, s30
	v_mov_b32_e32 v149, v109
	v_mov_b32_e32 v151, v109
	v_mov_b32_e32 v153, v109
	v_mov_b32_e32 v155, v109
	v_mov_b32_e32 v157, v109
	v_mov_b32_e32 v159, v109
	v_mov_b32_e32 v161, v109
	v_mov_b32_e32 v163, v109
	v_lshl_add_u64 v[80:81], v[140:141], 0, s[30:31]
	v_lshl_add_u64 v[82:83], v[0:1], 0, v[144:145]
	s_addc_u32 s53, s29, 0
	v_lshl_add_u64 v[100:101], s[0:1], 0, v[148:149]
	v_lshl_add_u64 v[102:103], s[0:1], 0, v[150:151]
	v_lshl_add_u64 v[104:105], s[0:1], 0, v[152:153]
	v_lshl_add_u64 v[164:165], s[0:1], 0, v[154:155]
	v_lshl_add_u64 v[166:167], s[0:1], 0, v[156:157]
	v_lshl_add_u64 v[168:169], s[0:1], 0, v[158:159]
	v_lshl_add_u64 v[170:171], s[0:1], 0, v[160:161]
	v_lshl_add_u64 v[172:173], s[0:1], 0, v[162:163]
	s_mov_b32 s16, 0
	s_mov_b64 s[0:1], -1
	s_cmp_ge_i32 s24, s69
	s_cselect_b32 s16, 32, 0
	s_cselect_b64 s[0:1], 0, -1
	s_branch .LBB0_840
